# in-proj GEMM: first K-iteration peeled with inline-0 SrcC (no 128-instruction accumulator zeroing per tile); on top of the attention trims
# baseline (speedup 1.0000x reference)
;     __device__ bool next(int i, Unit& u) const { const int t = c + i * nb; if (t >= 128) return false; u.pm = t & 31; u.pn = 88 + (t >> 5); return true; }
; #define PG8_STAGE(bufoff, gbase, voff) do { _Pragma("unroll") for (int _i = 0; _i < 2; ++_i) \
;         __builtin_amdgcn_global_load_lds((const unsigned*)((const char*)(gbase) + (voff)[_i]), (PG8_LAS unsigned*)(lds + (bufoff) + ldsw + _i * 8192), 16, 0, 0); } while (0)
; #define PG8_LDA(dst, b, h) do { _Pragma("unroll") for (int m = 0; m < 4; ++m) _Pragma("unroll") for (int k = 0; k < 2; ++k) dst[m][k] = *(const PG8_LAS bf16x8*)(lds + PG8_SA(b, h) + aoff + m * 2048 + k * 1024); } while (0)
; #define PG8_LDB(dst, b, h) do { _Pragma("unroll") for (int n = 0; n < 2; ++n) _Pragma("unroll") for (int k = 0; k < 2; ++k) dst[n][k] = *(const PG8_LAS bf16x8*)(lds + PG8_SB(b, h) + boff + n * 2048 + k * 1024); } while (0)
; #define PG8_WAIT_V(n) asm volatile("s_waitcnt vmcnt(" #n ")" ::: "memory")
; #define PG8_BAR __builtin_amdgcn_s_barrier()
; template <class Epi, class Sched, bool ALIGN_EPI = false, bool SP2 = false>
; __device__ __forceinline__ void gemm_phase(PG8_LAS unsigned char* lds, const Gemm g, const Sched& S, const Epi& E) {
;     ...
;         const bool has_next = S.next(ui + 1, nxt);
;         const char* nA = has_next ? (const char*)g.A + (size_t)nxt.pm * tstep : cA; const char* nB = has_next ? (const char*)g.Bt + (size_t)nxt.pn * tstep : cB;
;         for (int t = 0; t < nt; t += 2) {
;             const bool last = (t == nt - 2);
;             const char* a1 = cA + (size_t)(t + 1) * kstep;
;             const char* a2 = last ? nA : cA + (size_t)(t + 2) * kstep; const char* b2 = last ? nB : cB + (size_t)(t + 2) * kstep;
;             const char* a3 = a2 + kstep; const char* b3 = b2 + kstep;
;             if (last && has_next) S.a_ready(nxt);
;             if constexpr (SP2) {
;             PG8_LDB(B0, 0, 0); PG8_LDB(B1, 0, 1); PG8_SCHED; PG8_LDA(At, 0, 0); PG8_STAGE(PG8_SA(1, 1), a1 + hstep, voffA);
;             PG8_WAIT_V(8); PG8_WAIT_L(0); PG8_BAR; PG8_MMA(0, 0, At, B0); PG8_MMA(0, 1, At, B1); PG8_BAR; PG8_SCHED;
;             PG8_LDA(At, 0, 1); PG8_STAGE(PG8_SB(0, 0), b2, voffB); PG8_STAGE(PG8_SB(0, 1), b2 + hstep, voffB); PG8_STAGE(PG8_SA(0, 0), a2, voffA);
;             PG8_WAIT_V(8); PG8_WAIT_L(0); PG8_BAR; PG8_MMA(1, 0, At, B0); PG8_MMA(1, 1, At, B1); PG8_BAR; PG8_SCHED;
.LBB0_227:
	s_ashr_i32 s17, s16, 31
	s_lshl_b64 s[18:19], s[16:17], 20
	s_add_u32 s18, s24, s18
	s_addc_u32 s19, s25, s19
	s_and_b64 s[20:21], s[6:7], exec
	s_cselect_b32 s17, s19, s5
	s_cselect_b32 s40, s18, s4
	s_ashr_i32 s15, s14, 31
	s_lshl_b64 s[20:21], s[14:15], 20
	s_add_u32 s20, s26, s20
	s_addc_u32 s21, s27, s21
	s_and_b64 s[22:23], s[6:7], exec
	s_cselect_b32 s15, s21, s1
	s_cselect_b32 s41, s20, s0
	s_add_u32 s22, s4, 0x80080
	s_addc_u32 s23, s5, 0
	s_add_u32 s42, s0, 0x100
	s_addc_u32 s43, s1, 0
	s_mov_b32 s47, -2
	v_add_u32_e32 v144, 0x10000, v146
.Lg1_peel:
	s_add_u32 s0, s22, 0xfff80080
	s_addc_u32 s1, s23, -1
	s_cmp_eq_u32 s47, 28
	s_cselect_b32 s5, s17, s1
	s_cselect_b32 s4, s40, s0
	s_cselect_b32 s1, s15, s43
	s_cselect_b32 s0, s41, s42
	s_add_u32 s48, s0, 0x80000
	s_addc_u32 s49, s1, 0
	s_add_u32 s98, s0, 0x80
	s_addc_u32 s99, s1, 0
	ds_read_b128 v[148:151], v144 offset:0
	ds_read_b128 v[152:155], v144 offset:1024
	ds_read_b128 v[156:159], v144 offset:2048
	ds_read_b128 v[160:163], v144 offset:3072
	ds_read_b128 v[164:167], v144 offset:16384
	ds_read_b128 v[168:171], v144 offset:17408
	ds_read_b128 v[172:175], v144 offset:18432
	ds_read_b128 v[176:179], v144 offset:19456
	ds_read_b128 v[180:183], v147 offset:0
	ds_read_b128 v[184:187], v147 offset:1024
	ds_read_b128 v[188:191], v147 offset:2048
	ds_read_b128 v[192:195], v147 offset:3072
	ds_read_b128 v[206:209], v147 offset:4096
	ds_read_b128 v[210:213], v147 offset:5120
	ds_read_b128 v[214:217], v147 offset:6144
	ds_read_b128 v[218:221], v147 offset:7168
	s_add_i32 m0, s29, 0xc000
	s_nop 0
	global_load_lds_dwordx4 v138, s[22:23]
	s_add_i32 m0, s29, 0xe000
	s_nop 0
	global_load_lds_dwordx4 v140, s[22:23]
	s_waitcnt vmcnt(8)
	s_waitcnt lgkmcnt(0)
	s_barrier
	v_mfma_f32_16x16x32_bf16 v[126:129], v[148:151], v[180:183], 0
	v_mfma_f32_16x16x32_bf16 v[122:125], v[156:159], v[180:183], 0
	v_mfma_f32_16x16x32_bf16 v[114:117], v[148:151], v[188:191], 0
	v_mfma_f32_16x16x32_bf16 v[106:109], v[156:159], v[188:191], 0
	v_mfma_f32_16x16x32_bf16 v[98:101], v[148:151], v[206:209], 0
	v_mfma_f32_16x16x32_bf16 v[90:93], v[156:159], v[206:209], 0
	v_mfma_f32_16x16x32_bf16 v[82:85], v[148:151], v[214:217], 0
	v_mfma_f32_16x16x32_bf16 v[74:77], v[156:159], v[214:217], 0
	v_mfma_f32_16x16x32_bf16 v[126:129], v[152:155], v[184:187], v[126:129]
	v_mfma_f32_16x16x32_bf16 v[122:125], v[160:163], v[184:187], v[122:125]
	v_mfma_f32_16x16x32_bf16 v[114:117], v[152:155], v[192:195], v[114:117]
	v_mfma_f32_16x16x32_bf16 v[106:109], v[160:163], v[192:195], v[106:109]
	v_mfma_f32_16x16x32_bf16 v[98:101], v[152:155], v[210:213], v[98:101]
	v_mfma_f32_16x16x32_bf16 v[90:93], v[160:163], v[210:213], v[90:93]
	v_mfma_f32_16x16x32_bf16 v[82:85], v[152:155], v[218:221], v[82:85]
	v_mfma_f32_16x16x32_bf16 v[74:77], v[160:163], v[218:221], v[74:77]
	v_mfma_f32_16x16x32_bf16 v[118:121], v[164:167], v[180:183], 0
	v_mfma_f32_16x16x32_bf16 v[110:113], v[172:175], v[180:183], 0
	v_mfma_f32_16x16x32_bf16 v[102:105], v[164:167], v[188:191], 0
	v_mfma_f32_16x16x32_bf16 v[94:97], v[172:175], v[188:191], 0
	v_mfma_f32_16x16x32_bf16 v[86:89], v[164:167], v[206:209], 0
	v_mfma_f32_16x16x32_bf16 v[78:81], v[172:175], v[206:209], 0
	v_mfma_f32_16x16x32_bf16 v[70:73], v[164:167], v[214:217], 0
	v_mfma_f32_16x16x32_bf16 v[66:69], v[172:175], v[214:217], 0
	v_mfma_f32_16x16x32_bf16 v[118:121], v[168:171], v[184:187], v[118:121]
	v_mfma_f32_16x16x32_bf16 v[110:113], v[176:179], v[184:187], v[110:113]
	v_mfma_f32_16x16x32_bf16 v[102:105], v[168:171], v[192:195], v[102:105]
	v_mfma_f32_16x16x32_bf16 v[94:97], v[176:179], v[192:195], v[94:97]
	v_mfma_f32_16x16x32_bf16 v[86:89], v[168:171], v[210:213], v[86:89]
	v_mfma_f32_16x16x32_bf16 v[78:81], v[176:179], v[210:213], v[78:81]
	v_mfma_f32_16x16x32_bf16 v[70:73], v[168:171], v[218:221], v[70:73]
	v_mfma_f32_16x16x32_bf16 v[66:69], v[176:179], v[218:221], v[66:69]
	s_barrier
	ds_read_b128 v[180:183], v147 offset:16384
	ds_read_b128 v[184:187], v147 offset:17408
	ds_read_b128 v[188:191], v147 offset:18432
	ds_read_b128 v[192:195], v147 offset:19456
	ds_read_b128 v[206:209], v147 offset:20480
	ds_read_b128 v[210:213], v147 offset:21504
	ds_read_b128 v[214:217], v147 offset:22528
	ds_read_b128 v[218:221], v147 offset:23552
	s_add_i32 m0, s29, 0x10000
	s_nop 0
	global_load_lds_dwordx4 v0, s[0:1]
	s_add_i32 m0, s29, 0x12000
	s_nop 0
	global_load_lds_dwordx4 v130, s[0:1]
	s_add_i32 m0, s29, 0x14000
	s_nop 0
	global_load_lds_dwordx4 v0, s[48:49]
	s_add_i32 m0, s29, 0x16000
	s_nop 0
	global_load_lds_dwordx4 v130, s[48:49]
	s_add_i32 m0, s29, 0x0
	s_nop 0
	global_load_lds_dwordx4 v134, s[4:5]
	s_add_i32 m0, s29, 0x2000
	s_nop 0
	global_load_lds_dwordx4 v132, s[4:5]
	s_waitcnt vmcnt(8)
	s_waitcnt lgkmcnt(0)
	s_barrier
; #define PG8_STAGE(bufoff, gbase, voff) do { _Pragma("unroll") for (int _i = 0; _i < 2; ++_i) \
;         __builtin_amdgcn_global_load_lds((const unsigned*)((const char*)(gbase) + (voff)[_i]), (PG8_LAS unsigned*)(lds + (bufoff) + ldsw + _i * 8192), 16, 0, 0); } while (0)
; #define PG8_LDA(dst, b, h) do { _Pragma("unroll") for (int m = 0; m < 4; ++m) _Pragma("unroll") for (int k = 0; k < 2; ++k) dst[m][k] = *(const PG8_LAS bf16x8*)(lds + PG8_SA(b, h) + aoff + m * 2048 + k * 1024); } while (0)
; #define PG8_LDB(dst, b, h) do { _Pragma("unroll") for (int n = 0; n < 2; ++n) _Pragma("unroll") for (int k = 0; k < 2; ++k) dst[n][k] = *(const PG8_LAS bf16x8*)(lds + PG8_SB(b, h) + boff + n * 2048 + k * 1024); } while (0)
; #define PG8_MMA(ai, bj, At, Bt) do { __builtin_amdgcn_s_setprio(1); _Pragma("unroll") for (int m = 0; m < 4; ++m) _Pragma("unroll") for (int n = 0; n < 2; ++n) _Pragma("unroll") for (int k = 0; k < 2; ++k) \
;         acc[ai][bj][m][n] = __builtin_amdgcn_mfma_f32_16x16x32_bf16(Bt[n][k], At[m][k], acc[ai][bj][m][n], 0, 0, 0); __builtin_amdgcn_s_setprio(0); } while (0)
; #define PG8_WAIT_V(n) asm volatile("s_waitcnt vmcnt(" #n ")" ::: "memory")
; #define PG8_WAIT_L(n) asm volatile("s_waitcnt lgkmcnt(" #n ")" ::: "memory")
; #define PG8_BAR __builtin_amdgcn_s_barrier()
; #define PG8_SCHED __builtin_amdgcn_sched_barrier(0)
; template <class Epi, class Sched, bool ALIGN_EPI = false, bool SP2 = false>
; __device__ __forceinline__ void gemm_phase(PG8_LAS unsigned char* lds, const Gemm g, const Sched& S, const Epi& E) {
;     ...
;             PG8_WAIT_V(8); PG8_WAIT_L(0); PG8_BAR; PG8_MMA(1, 0, At, B0); PG8_MMA(1, 1, At, B1); PG8_BAR; PG8_SCHED;
;             PG8_LDB(B0, 1, 0); PG8_LDB(B1, 1, 1); PG8_SCHED; PG8_LDA(At, 1, 0); PG8_STAGE(PG8_SA(0, 1), a2 + hstep, voffA);
;             PG8_WAIT_V(8); PG8_WAIT_L(0); PG8_BAR; PG8_MMA(0, 0, At, B0); PG8_MMA(0, 1, At, B1); PG8_BAR; PG8_SCHED;
;             PG8_LDA(At, 1, 1); PG8_STAGE(PG8_SB(1, 0), b3, voffB); PG8_STAGE(PG8_SB(1, 1), b3 + hstep, voffB); PG8_STAGE(PG8_SA(1, 0), a3, voffA);
;             PG8_WAIT_V(8); PG8_WAIT_L(0); PG8_BAR; PG8_MMA(1, 0, At, B0); PG8_MMA(1, 1, At, B1); PG8_BAR; PG8_SCHED;
	v_mfma_f32_16x16x32_bf16 v[62:65], v[148:151], v[180:183], 0
	v_mfma_f32_16x16x32_bf16 v[58:61], v[156:159], v[180:183], 0
	v_mfma_f32_16x16x32_bf16 v[50:53], v[148:151], v[188:191], 0
	v_mfma_f32_16x16x32_bf16 v[42:45], v[156:159], v[188:191], 0
	v_mfma_f32_16x16x32_bf16 v[34:37], v[148:151], v[206:209], 0
	v_mfma_f32_16x16x32_bf16 v[26:29], v[156:159], v[206:209], 0
	v_mfma_f32_16x16x32_bf16 v[18:21], v[148:151], v[214:217], 0
	v_mfma_f32_16x16x32_bf16 v[10:13], v[156:159], v[214:217], 0
	v_mfma_f32_16x16x32_bf16 v[62:65], v[152:155], v[184:187], v[62:65]
	v_mfma_f32_16x16x32_bf16 v[58:61], v[160:163], v[184:187], v[58:61]
	v_mfma_f32_16x16x32_bf16 v[50:53], v[152:155], v[192:195], v[50:53]
	v_mfma_f32_16x16x32_bf16 v[42:45], v[160:163], v[192:195], v[42:45]
	v_mfma_f32_16x16x32_bf16 v[34:37], v[152:155], v[210:213], v[34:37]
	v_mfma_f32_16x16x32_bf16 v[26:29], v[160:163], v[210:213], v[26:29]
	v_mfma_f32_16x16x32_bf16 v[18:21], v[152:155], v[218:221], v[18:21]
	v_mfma_f32_16x16x32_bf16 v[10:13], v[160:163], v[218:221], v[10:13]
	v_mfma_f32_16x16x32_bf16 v[54:57], v[164:167], v[180:183], 0
	v_mfma_f32_16x16x32_bf16 v[46:49], v[172:175], v[180:183], 0
	v_mfma_f32_16x16x32_bf16 v[38:41], v[164:167], v[188:191], 0
	v_mfma_f32_16x16x32_bf16 v[30:33], v[172:175], v[188:191], 0
	v_mfma_f32_16x16x32_bf16 v[22:25], v[164:167], v[206:209], 0
	v_mfma_f32_16x16x32_bf16 v[14:17], v[172:175], v[206:209], 0
	v_mfma_f32_16x16x32_bf16 v[6:9], v[164:167], v[214:217], 0
	v_mfma_f32_16x16x32_bf16 v[2:5], v[172:175], v[214:217], 0
	v_mfma_f32_16x16x32_bf16 v[54:57], v[168:171], v[184:187], v[54:57]
	v_mfma_f32_16x16x32_bf16 v[46:49], v[176:179], v[184:187], v[46:49]
	v_mfma_f32_16x16x32_bf16 v[38:41], v[168:171], v[192:195], v[38:41]
	v_mfma_f32_16x16x32_bf16 v[30:33], v[176:179], v[192:195], v[30:33]
	v_mfma_f32_16x16x32_bf16 v[22:25], v[168:171], v[210:213], v[22:25]
	v_mfma_f32_16x16x32_bf16 v[14:17], v[176:179], v[210:213], v[14:17]
	v_mfma_f32_16x16x32_bf16 v[6:9], v[168:171], v[218:221], v[6:9]
	v_mfma_f32_16x16x32_bf16 v[2:5], v[176:179], v[218:221], v[2:5]
	s_barrier
	s_add_u32 s4, s4, 0x80000
	s_addc_u32 s5, s5, 0
	s_add_u32 s0, s0, 0x80080
	s_addc_u32 s1, s1, 0
	ds_read_b128 v[148:151], v144 offset:32768
	ds_read_b128 v[152:155], v144 offset:33792
	ds_read_b128 v[156:159], v144 offset:34816
	ds_read_b128 v[160:163], v144 offset:35840
	ds_read_b128 v[164:167], v144 offset:49152
	ds_read_b128 v[168:171], v144 offset:50176
	ds_read_b128 v[172:175], v144 offset:51200
	ds_read_b128 v[176:179], v144 offset:52224
	ds_read_b128 v[180:183], v147 offset:32768
	ds_read_b128 v[184:187], v147 offset:33792
	ds_read_b128 v[188:191], v147 offset:34816
	ds_read_b128 v[192:195], v147 offset:35840
	ds_read_b128 v[206:209], v147 offset:36864
	ds_read_b128 v[210:213], v147 offset:37888
	ds_read_b128 v[214:217], v147 offset:38912
	ds_read_b128 v[218:221], v147 offset:39936
	s_add_i32 m0, s29, 0x4000
	s_nop 0
	global_load_lds_dwordx4 v134, s[4:5]
	s_add_i32 m0, s29, 0x6000
	s_nop 0
	global_load_lds_dwordx4 v132, s[4:5]
	s_waitcnt vmcnt(8)
	s_waitcnt lgkmcnt(0)
	s_barrier
	v_mfma_f32_16x16x32_bf16 v[126:129], v[148:151], v[180:183], v[126:129]
	v_mfma_f32_16x16x32_bf16 v[122:125], v[156:159], v[180:183], v[122:125]
	v_mfma_f32_16x16x32_bf16 v[114:117], v[148:151], v[188:191], v[114:117]
	v_mfma_f32_16x16x32_bf16 v[106:109], v[156:159], v[188:191], v[106:109]
	v_mfma_f32_16x16x32_bf16 v[98:101], v[148:151], v[206:209], v[98:101]
	v_mfma_f32_16x16x32_bf16 v[90:93], v[156:159], v[206:209], v[90:93]
	v_mfma_f32_16x16x32_bf16 v[82:85], v[148:151], v[214:217], v[82:85]
	v_mfma_f32_16x16x32_bf16 v[74:77], v[156:159], v[214:217], v[74:77]
	v_mfma_f32_16x16x32_bf16 v[126:129], v[152:155], v[184:187], v[126:129]
	v_mfma_f32_16x16x32_bf16 v[122:125], v[160:163], v[184:187], v[122:125]
	v_mfma_f32_16x16x32_bf16 v[114:117], v[152:155], v[192:195], v[114:117]
	v_mfma_f32_16x16x32_bf16 v[106:109], v[160:163], v[192:195], v[106:109]
	v_mfma_f32_16x16x32_bf16 v[98:101], v[152:155], v[210:213], v[98:101]
	v_mfma_f32_16x16x32_bf16 v[90:93], v[160:163], v[210:213], v[90:93]
	v_mfma_f32_16x16x32_bf16 v[82:85], v[152:155], v[218:221], v[82:85]
	v_mfma_f32_16x16x32_bf16 v[74:77], v[160:163], v[218:221], v[74:77]
	v_mfma_f32_16x16x32_bf16 v[118:121], v[164:167], v[180:183], v[118:121]
	v_mfma_f32_16x16x32_bf16 v[110:113], v[172:175], v[180:183], v[110:113]
	v_mfma_f32_16x16x32_bf16 v[102:105], v[164:167], v[188:191], v[102:105]
	v_mfma_f32_16x16x32_bf16 v[94:97], v[172:175], v[188:191], v[94:97]
	v_mfma_f32_16x16x32_bf16 v[86:89], v[164:167], v[206:209], v[86:89]
	v_mfma_f32_16x16x32_bf16 v[78:81], v[172:175], v[206:209], v[78:81]
	v_mfma_f32_16x16x32_bf16 v[70:73], v[164:167], v[214:217], v[70:73]
	v_mfma_f32_16x16x32_bf16 v[66:69], v[172:175], v[214:217], v[66:69]
	v_mfma_f32_16x16x32_bf16 v[118:121], v[168:171], v[184:187], v[118:121]
	v_mfma_f32_16x16x32_bf16 v[110:113], v[176:179], v[184:187], v[110:113]
	v_mfma_f32_16x16x32_bf16 v[102:105], v[168:171], v[192:195], v[102:105]
	v_mfma_f32_16x16x32_bf16 v[94:97], v[176:179], v[192:195], v[94:97]
	v_mfma_f32_16x16x32_bf16 v[86:89], v[168:171], v[210:213], v[86:89]
	v_mfma_f32_16x16x32_bf16 v[78:81], v[176:179], v[210:213], v[78:81]
	v_mfma_f32_16x16x32_bf16 v[70:73], v[168:171], v[218:221], v[70:73]
	v_mfma_f32_16x16x32_bf16 v[66:69], v[176:179], v[218:221], v[66:69]
	s_barrier
; #define PG8_STAGE(bufoff, gbase, voff) do { _Pragma("unroll") for (int _i = 0; _i < 2; ++_i) \
;         __builtin_amdgcn_global_load_lds((const unsigned*)((const char*)(gbase) + (voff)[_i]), (PG8_LAS unsigned*)(lds + (bufoff) + ldsw + _i * 8192), 16, 0, 0); } while (0)
; #define PG8_LDA(dst, b, h) do { _Pragma("unroll") for (int m = 0; m < 4; ++m) _Pragma("unroll") for (int k = 0; k < 2; ++k) dst[m][k] = *(const PG8_LAS bf16x8*)(lds + PG8_SA(b, h) + aoff + m * 2048 + k * 1024); } while (0)
; #define PG8_MMA(ai, bj, At, Bt) do { __builtin_amdgcn_s_setprio(1); _Pragma("unroll") for (int m = 0; m < 4; ++m) _Pragma("unroll") for (int n = 0; n < 2; ++n) _Pragma("unroll") for (int k = 0; k < 2; ++k) \
;         acc[ai][bj][m][n] = __builtin_amdgcn_mfma_f32_16x16x32_bf16(Bt[n][k], At[m][k], acc[ai][bj][m][n], 0, 0, 0); __builtin_amdgcn_s_setprio(0); } while (0)
; #define PG8_WAIT_V(n) asm volatile("s_waitcnt vmcnt(" #n ")" ::: "memory")
; #define PG8_WAIT_L(n) asm volatile("s_waitcnt lgkmcnt(" #n ")" ::: "memory")
; #define PG8_BAR __builtin_amdgcn_s_barrier()
; #define PG8_SCHED __builtin_amdgcn_sched_barrier(0)
; template <class Epi, class Sched, bool ALIGN_EPI = false, bool SP2 = false>
; __device__ __forceinline__ void gemm_phase(PG8_LAS unsigned char* lds, const Gemm g, const Sched& S, const Epi& E) {
;     ...
;         for (int t = 0; t < nt; t += 2) {
;     ...
;             PG8_LDA(At, 1, 1); PG8_STAGE(PG8_SB(1, 0), b3, voffB); PG8_STAGE(PG8_SB(1, 1), b3 + hstep, voffB); PG8_STAGE(PG8_SA(1, 0), a3, voffA);
;             PG8_WAIT_V(8); PG8_WAIT_L(0); PG8_BAR; PG8_MMA(1, 0, At, B0); PG8_MMA(1, 1, At, B1); PG8_BAR; PG8_SCHED;
	s_add_u32 s4, s4, 0xfff80080
	s_addc_u32 s5, s5, -1
	ds_read_b128 v[180:183], v147 offset:49152
	ds_read_b128 v[184:187], v147 offset:50176
	ds_read_b128 v[188:191], v147 offset:51200
	ds_read_b128 v[192:195], v147 offset:52224
	ds_read_b128 v[206:209], v147 offset:53248
	ds_read_b128 v[210:213], v147 offset:54272
	ds_read_b128 v[214:217], v147 offset:55296
	ds_read_b128 v[218:221], v147 offset:56320
	s_add_i32 m0, s29, 0x18000
	s_nop 0
	global_load_lds_dwordx4 v0, s[98:99]
	s_add_i32 m0, s29, 0x1a000
	s_nop 0
	global_load_lds_dwordx4 v130, s[98:99]
	s_add_i32 m0, s29, 0x1c000
	s_nop 0
	global_load_lds_dwordx4 v0, s[0:1]
	s_add_i32 m0, s29, 0x1e000
	s_nop 0
	global_load_lds_dwordx4 v130, s[0:1]
	s_add_i32 m0, s29, 0x8000
	s_nop 0
	global_load_lds_dwordx4 v134, s[4:5]
	s_add_i32 m0, s29, 0xa000
	s_nop 0
	global_load_lds_dwordx4 v132, s[4:5]
	s_waitcnt vmcnt(8)
	s_waitcnt lgkmcnt(0)
	s_barrier
	v_mfma_f32_16x16x32_bf16 v[62:65], v[148:151], v[180:183], v[62:65]
	v_mfma_f32_16x16x32_bf16 v[58:61], v[156:159], v[180:183], v[58:61]
	v_mfma_f32_16x16x32_bf16 v[50:53], v[148:151], v[188:191], v[50:53]
	v_mfma_f32_16x16x32_bf16 v[42:45], v[156:159], v[188:191], v[42:45]
	v_mfma_f32_16x16x32_bf16 v[34:37], v[148:151], v[206:209], v[34:37]
	v_mfma_f32_16x16x32_bf16 v[26:29], v[156:159], v[206:209], v[26:29]
	v_mfma_f32_16x16x32_bf16 v[18:21], v[148:151], v[214:217], v[18:21]
	v_mfma_f32_16x16x32_bf16 v[10:13], v[156:159], v[214:217], v[10:13]
	v_mfma_f32_16x16x32_bf16 v[62:65], v[152:155], v[184:187], v[62:65]
	v_mfma_f32_16x16x32_bf16 v[58:61], v[160:163], v[184:187], v[58:61]
	v_mfma_f32_16x16x32_bf16 v[50:53], v[152:155], v[192:195], v[50:53]
	v_mfma_f32_16x16x32_bf16 v[42:45], v[160:163], v[192:195], v[42:45]
	v_mfma_f32_16x16x32_bf16 v[34:37], v[152:155], v[210:213], v[34:37]
	v_mfma_f32_16x16x32_bf16 v[26:29], v[160:163], v[210:213], v[26:29]
	v_mfma_f32_16x16x32_bf16 v[18:21], v[152:155], v[218:221], v[18:21]
	v_mfma_f32_16x16x32_bf16 v[10:13], v[160:163], v[218:221], v[10:13]
	v_mfma_f32_16x16x32_bf16 v[54:57], v[164:167], v[180:183], v[54:57]
	v_mfma_f32_16x16x32_bf16 v[46:49], v[172:175], v[180:183], v[46:49]
	v_mfma_f32_16x16x32_bf16 v[38:41], v[164:167], v[188:191], v[38:41]
	v_mfma_f32_16x16x32_bf16 v[30:33], v[172:175], v[188:191], v[30:33]
	v_mfma_f32_16x16x32_bf16 v[22:25], v[164:167], v[206:209], v[22:25]
	v_mfma_f32_16x16x32_bf16 v[14:17], v[172:175], v[206:209], v[14:17]
	v_mfma_f32_16x16x32_bf16 v[6:9], v[164:167], v[214:217], v[6:9]
	v_mfma_f32_16x16x32_bf16 v[2:5], v[172:175], v[214:217], v[2:5]
	v_mfma_f32_16x16x32_bf16 v[54:57], v[168:171], v[184:187], v[54:57]
	v_mfma_f32_16x16x32_bf16 v[46:49], v[176:179], v[184:187], v[46:49]
	v_mfma_f32_16x16x32_bf16 v[38:41], v[168:171], v[192:195], v[38:41]
	v_mfma_f32_16x16x32_bf16 v[30:33], v[176:179], v[192:195], v[30:33]
	v_mfma_f32_16x16x32_bf16 v[22:25], v[168:171], v[210:213], v[22:25]
	v_mfma_f32_16x16x32_bf16 v[14:17], v[176:179], v[210:213], v[14:17]
	v_mfma_f32_16x16x32_bf16 v[6:9], v[168:171], v[218:221], v[6:9]
	v_mfma_f32_16x16x32_bf16 v[2:5], v[176:179], v[218:221], v[2:5]
	s_barrier
	s_add_i32 s47, s47, 2
	s_add_u32 s22, s22, 0x100
	s_addc_u32 s23, s23, 0
	s_add_u32 s42, s42, 0x100
	s_addc_u32 s43, s43, 0
